# main NA tile loop: Q fragments kept in registers v[198:229] instead of re-reading them from the LDS park every tile (8 fewer ds_read_b128 per tile per wave)
# speedup vs baseline: 1.0055x; 1.0055x over previous
; __device__ __forceinline__ int v_st(int k, int c) { const int kk = (k & ~0xC) | ((k & 4) << 1) | ((k & 8) >> 1); return ((kk >> 3) * 4 + (c >> 5)) * 512 + ((kk & 7) * 32 + (c & 31)) * 2; }
; __device__ __forceinline__ int v_rd_base(int lane) { return ((lane & 3) << 3) | (((lane >> 2) & 3) << 6) | (((lane >> 4) & 1) << 5) | (((lane >> 5) & 1) << 8); }
; #define NA_SLOAD(j) do { const long _k0 = NA_TROW(j); vs0 = *reinterpret_cast<const bf16x8*>(&Vh[(_k0 + sr) * LDP + sc]); vs1 = *reinterpret_cast<const bf16x8*>(&Vh[(_k0 + 32 + sr) * LDP + sc]); \
;     ks0 = *reinterpret_cast<const bf16x8*>(&Kh[(_k0 + sr) * LDP + sc]); ks1 = *reinterpret_cast<const bf16x8*>(&Kh[(_k0 + 32 + sr) * LDP + sc]); } while (0)
; template <int LDP, int LDO> ...
;     ...
;     if (tid < 128) pens[tid] = (tid >= 48 && tid < 64) ? 0.f : NEG;
;   }
;   float m_reg = -1e30f, l_reg = 0; f32x16 o[4] = {};
;   bf16x8* qs = (bf16x8*)(lds + QS_OFF + wid * 8192) + lane;
;   { const bf16* Qw = P + (qrow0 + wid * QBLK + r32) * LDP + qcol + hi * 8;
; #pragma unroll
;     for (int d0 = 0; d0 < 8; ++d0) qs[d0 * 64] = *reinterpret_cast<const bf16x8*>(Qw + d0 * 16); }
;   const int sr = tid >> 4, sc = (tid & 15) * 8, vst0 = v_st(sr, sc), vst1 = v_st(32 + sr, sc);
;   const int vb0 = (int)(uintptr_t)V_lds + v_rd_base(lane);
;   const int qrow = qg0 + (wid >> 1), qc = (wid & 1) * 32 + r32;
;   const float* bt_l = blds + 64 + 15 - qc + 4 * hi; const float* pen_l = pens + 48 - min(max(qc - 8, 0), 48) + 4 * hi;
;   const bf16* Kh = P + kcol; const bf16* Vh = P + vcol;
;   bf16x8 vs0, vs1, ks0, ks1;
;     ...
;   f32x16 p0, p1; float mn, al; bf16x8 pa0, pa1, pa2, pa3; const int NT = 4 + nband; const int rs_ = min(max(qrow - 4, 0), 56);
;   NA_SLOAD(0);
.LBB0_705:
	s_or_b64 exec, exec, s[0:1]
	s_and_saveexec_b64 s[0:1], s[42:43]
	ds_write_b32 v123, v117
	s_or_b64 exec, exec, s[0:1]
	s_and_b32 s10, s54, 15
	s_and_b32 s0, s53, 15
	s_lshl_b32 s51, s10, 2
	s_lshl_b32 s50, s0, 9
	s_ashr_i32 s0, s54, 7
	s_add_i32 s1, s51, -4
	s_cmp_eq_u32 s10, 0
	s_cselect_b64 s[4:5], -1, 0
	s_and_b64 s[8:9], s[4:5], exec
	s_cselect_b32 s57, 0, s1
	s_cmp_eq_u32 s10, 15
	s_cselect_b64 s[8:9], -1, 0
	s_ashr_i32 s1, s0, 31
	s_or_b64 s[12:13], s[4:5], s[8:9]
	s_lshl_b64 s[8:9], s[0:1], 12
	s_lshl_b32 s1, s10, 8
	s_lshl_b32 s4, s0, 8
	s_lshl_b32 s20, s18, 7
	s_or_b32 s10, s8, s1
	s_mov_b32 s11, s9
	s_ashr_i32 s5, s4, 31
	s_add_u32 s22, s4, 0x4000
	v_lshl_add_u64 v[130:131], s[10:11], 0, v[118:119]
	s_addc_u32 s23, s5, 0
	s_lshl_b32 s0, s57, 6
	v_or_b32_e32 v6, v130, v116
	v_mov_b64_e32 v[4:5], s[6:7]
	s_movk_i32 s3, 0x3200
	s_add_u32 s8, s8, s0
	v_mad_u64_u32 v[4:5], s[0:1], v6, s3, v[4:5]
	s_addc_u32 s9, s9, 0
	v_mad_i32_i24 v5, v131, s3, v5
	s_lshl_b32 s30, s18, 8
	v_lshl_add_u64 v[4:5], v[4:5], 0, s[30:31]
	v_mov_b32_e32 v129, v3
	v_lshl_add_u64 v[4:5], v[4:5], 0, v[128:129]
	global_load_dwordx4 v[198:201], v[4:5], off
	global_load_dwordx4 v[202:205], v[4:5], off offset:32
	global_load_dwordx4 v[206:209], v[4:5], off offset:64
	global_load_dwordx4 v[210:213], v[4:5], off offset:96
	global_load_dwordx4 v[214:217], v[4:5], off offset:128
	global_load_dwordx4 v[218:221], v[4:5], off offset:160
	global_load_dwordx4 v[222:225], v[4:5], off offset:192
	global_load_dwordx4 v[226:229], v[4:5], off offset:224
	s_add_u32 s0, s6, s30
	v_lshl_add_u64 v[4:5], s[22:23], 0, v[120:121]
	s_addc_u32 s1, s7, 0
	v_mad_u64_u32 v[6:7], s[18:19], v4, s34, 0
	v_lshl_add_u64 v[8:9], v[124:125], 0, s[4:5]
	s_add_u32 s10, s0, 0x1000
	v_mad_i32_i24 v5, v5, s34, v7
	v_or_b32_e32 v4, v6, v122
	v_mad_u64_u32 v[10:11], s[18:19], v8, s34, 0
	s_addc_u32 s11, s1, 0
	v_lshlrev_b64 v[4:5], 1, v[4:5]
	v_mad_i32_i24 v9, v9, s34, v11
	v_or_b32_e32 v8, v10, v122
	v_lshl_add_u64 v[6:7], s[10:11], 0, v[4:5]
	v_lshlrev_b64 v[8:9], 1, v[8:9]
	v_lshl_add_u64 v[4:5], s[0:1], 0, v[4:5]
	v_lshl_add_u64 v[10:11], s[10:11], 0, v[8:9]
	v_lshl_add_u64 v[8:9], s[0:1], 0, v[8:9]
	global_load_dwordx4 v[104:107], v[4:5], off offset:2048
	global_load_dwordx4 v[100:103], v[8:9], off offset:2048
	global_load_dwordx4 v[112:115], v[6:7], off
	global_load_dwordx4 v[108:111], v[10:11], off
	s_add_i32 s55, s57, -4
	s_and_b64 s[12:13], s[12:13], exec
	v_add_u32_e32 v159, s51, v135
	s_movk_i32 s12, 0x580
	v_max_i32_e32 v11, 4, v159
	s_cselect_b32 s56, s12, 0x780
	s_lshl_b32 s12, s57, 7
	v_add_u32_e32 v11, -4, v11
	s_sub_i32 s12, s12, s50
	v_mov_b32_e32 v4, v3
	v_mov_b32_e32 v5, v3
	v_mov_b32_e32 v6, v3
	v_mov_b32_e32 v7, v3
	v_mov_b32_e32 v8, v3
	v_mov_b32_e32 v9, v3
	v_mov_b32_e32 v10, v3
	v_min_u32_e32 v160, 56, v11
	v_add_u32_e32 v162, s12, v156
	s_add_u32 s12, s4, 0x4040
	v_mov_b32_e32 v11, v3
	s_mov_b32 s21, 0
	v_add_u32_e32 v161, 8, v160
	s_addc_u32 s13, s5, 0
	v_mov_b32_e32 v158, 0
	v_mov_b32_e32 v129, 0xf149f2ca
	s_mov_b32 s58, 0
	s_mov_b32 s57, 0
	s_waitcnt vmcnt(11)
	ds_write_b128 v157, v[198:201]
	s_waitcnt vmcnt(10)
	ds_write_b128 v157, v[202:205] offset:1024
	s_waitcnt vmcnt(9)
	ds_write_b128 v157, v[206:209] offset:2048
	s_waitcnt vmcnt(8)
	ds_write_b128 v157, v[210:213] offset:3072
	s_waitcnt vmcnt(7)
	ds_write_b128 v157, v[214:217] offset:4096
	s_waitcnt vmcnt(6)
	ds_write_b128 v157, v[218:221] offset:5120
	s_waitcnt vmcnt(5)
	ds_write_b128 v157, v[222:225] offset:6144
	s_waitcnt vmcnt(4)
	ds_write_b128 v157, v[226:229] offset:7168
	v_mov_b32_e32 v18, v3
	v_mov_b32_e32 v19, v3
	v_mov_b32_e32 v12, v3
	v_mov_b32_e32 v13, v3
	v_mov_b32_e32 v14, v3
	v_mov_b32_e32 v15, v3
	v_mov_b32_e32 v16, v3
	v_mov_b32_e32 v17, v3
	v_mov_b64_e32 v[66:67], v[18:19]
	v_mov_b64_e32 v[50:51], v[18:19]
	v_mov_b64_e32 v[34:35], v[18:19]
	v_mov_b64_e32 v[64:65], v[16:17]
	v_mov_b64_e32 v[62:63], v[14:15]
	v_mov_b64_e32 v[60:61], v[12:13]
	v_mov_b64_e32 v[58:59], v[10:11]
	v_mov_b64_e32 v[56:57], v[8:9]
	v_mov_b64_e32 v[54:55], v[6:7]
	v_mov_b64_e32 v[52:53], v[4:5]
	v_mov_b64_e32 v[48:49], v[16:17]
	v_mov_b64_e32 v[46:47], v[14:15]
	v_mov_b64_e32 v[44:45], v[12:13]
	v_mov_b64_e32 v[42:43], v[10:11]
	v_mov_b64_e32 v[40:41], v[8:9]
	v_mov_b64_e32 v[38:39], v[6:7]
	v_mov_b64_e32 v[36:37], v[4:5]
	v_mov_b64_e32 v[32:33], v[16:17]
	v_mov_b64_e32 v[30:31], v[14:15]
	v_mov_b64_e32 v[28:29], v[12:13]
	v_mov_b64_e32 v[26:27], v[10:11]
	v_mov_b64_e32 v[24:25], v[8:9]
	v_mov_b64_e32 v[22:23], v[6:7]
	v_mov_b64_e32 v[20:21], v[4:5]
	s_branch .LBB0_711

; __device__ __forceinline__ void partialSM(f32x16& p0, f32x16& p1, float& m_reg, float& mn, float& alpha) {
;     ...
;   float pmax = p0[0];
; #pragma unroll
;   for (int r = 1; r < 16; ++r) pmax = fmaxf(pmax, p0[r]);
; #pragma unroll
;   for (int r = 0; r < 16; ++r) pmax = fmaxf(pmax, p1[r]);
;   { auto rr = __builtin_amdgcn_permlane32_swap(__float_as_uint(pmax), __float_as_uint(pmax), false, false);
;     pmax = fmaxf(__uint_as_float(rr[0]), __uint_as_float(rr[1])); }
;   if (__builtin_expect(__all(pmax - m_reg <= THR / SCALE), 1)) { mn = m_reg; alpha = 1.f; }
;   else { mn = fmaxf(m_reg, pmax); alpha = __builtin_amdgcn_exp2f((m_reg - mn) * C); m_reg = mn; }
; __device__ __forceinline__ void qkt(f32x16& p0, f32x16& p1, const bf16* Ks, const bf16x8* qs, int r32, int hi) {
; #pragma unroll
;   for (int d0 = 0; d0 < 8; ++d0) { int cb = (d0 * 16 + hi * 8) * 2; const bf16x8 q = qs[d0 * 64];
;     bf16x8 b0 = *reinterpret_cast<const bf16x8*>((const char*)Ks + NA_KSWZ(r32, cb));
;     bf16x8 b1 = *reinterpret_cast<const bf16x8*>((const char*)Ks + NA_KSWZ(32 + r32, cb));
;     p0 = __builtin_amdgcn_mfma_f32_32x32x16_bf16(b0, q, p0, 0, 0, 0);
;     p1 = __builtin_amdgcn_mfma_f32_32x32x16_bf16(b1, q, p1, 0, 0, 0); }
; }
.LBB0_718:
	v_add3_u32 v163, s18, v142, v141
	ds_read_b128 v[168:171], v163 offset:32768
	ds_read_b128 v[172:175], v163 offset:40960
	v_add3_u32 v163, s18, v143, v141
	s_waitcnt lgkmcnt(1)
	v_mfma_f32_32x32x16_bf16 v[84:99], v[168:171], v[198:201], v[84:99]
	s_waitcnt lgkmcnt(0)
	v_mfma_f32_32x32x16_bf16 v[68:83], v[172:175], v[198:201], v[68:83]
	ds_read_b128 v[168:171], v163 offset:32768
	ds_read_b128 v[172:175], v163 offset:40960
	v_add3_u32 v163, s18, v144, v141
	s_waitcnt lgkmcnt(1)
	v_mfma_f32_32x32x16_bf16 v[84:99], v[168:171], v[202:205], v[84:99]
	s_waitcnt lgkmcnt(0)
	v_mfma_f32_32x32x16_bf16 v[68:83], v[172:175], v[202:205], v[68:83]
	ds_read_b128 v[168:171], v163 offset:32768
	ds_read_b128 v[172:175], v163 offset:40960
	v_add3_u32 v163, s18, v145, v141
	s_waitcnt lgkmcnt(1)
	v_mfma_f32_32x32x16_bf16 v[84:99], v[168:171], v[206:209], v[84:99]
	s_waitcnt lgkmcnt(0)
	v_mfma_f32_32x32x16_bf16 v[68:83], v[172:175], v[206:209], v[68:83]
	ds_read_b128 v[168:171], v163 offset:32768
	ds_read_b128 v[172:175], v163 offset:40960
	v_add3_u32 v163, s18, v146, v141
	s_waitcnt lgkmcnt(1)
	v_mfma_f32_32x32x16_bf16 v[84:99], v[168:171], v[210:213], v[84:99]
	s_waitcnt lgkmcnt(0)
	v_mfma_f32_32x32x16_bf16 v[68:83], v[172:175], v[210:213], v[68:83]
	ds_read_b128 v[168:171], v163 offset:32768
	ds_read_b128 v[172:175], v163 offset:40960
	v_add3_u32 v163, s18, v147, v141
	s_waitcnt lgkmcnt(1)
	v_mfma_f32_32x32x16_bf16 v[84:99], v[168:171], v[214:217], v[84:99]
	s_waitcnt lgkmcnt(0)
	v_mfma_f32_32x32x16_bf16 v[68:83], v[172:175], v[214:217], v[68:83]
	ds_read_b128 v[168:171], v163 offset:32768
	ds_read_b128 v[172:175], v163 offset:40960
	v_add3_u32 v163, s18, v148, v141
	s_waitcnt lgkmcnt(1)
	v_mfma_f32_32x32x16_bf16 v[84:99], v[168:171], v[218:221], v[84:99]
	s_waitcnt lgkmcnt(0)
	v_mfma_f32_32x32x16_bf16 v[68:83], v[172:175], v[218:221], v[68:83]
	ds_read_b128 v[168:171], v163 offset:32768
	ds_read_b128 v[172:175], v163 offset:40960
	v_add3_u32 v163, s18, v149, v141
	s_waitcnt lgkmcnt(1)
	v_mfma_f32_32x32x16_bf16 v[84:99], v[168:171], v[222:225], v[84:99]
	s_waitcnt lgkmcnt(0)
	v_mfma_f32_32x32x16_bf16 v[68:83], v[172:175], v[222:225], v[68:83]
	ds_read_b128 v[168:171], v163 offset:32768
	ds_read_b128 v[172:175], v163 offset:40960
	s_waitcnt lgkmcnt(1)
	v_mfma_f32_32x32x16_bf16 v[84:99], v[168:171], v[226:229], v[84:99]
	s_waitcnt lgkmcnt(0)
	v_mfma_f32_32x32x16_bf16 v[68:83], v[172:175], v[226:229], v[68:83]
	s_nop 9
	v_max_f32_e32 v163, v85, v85
	v_max_f32_e32 v164, v84, v84
	v_max_f32_e32 v163, v164, v163
	v_max3_f32 v163, v163, v86, v87
	v_max3_f32 v163, v163, v88, v89
	v_max3_f32 v163, v163, v90, v91
	v_max3_f32 v163, v163, v92, v93
	v_max3_f32 v163, v163, v94, v95
	v_max3_f32 v163, v163, v96, v97
	v_max3_f32 v163, v163, v98, v99
	v_max3_f32 v163, v163, v68, v69
	v_max3_f32 v163, v163, v70, v71
	v_max3_f32 v163, v163, v72, v73
	v_max3_f32 v163, v163, v74, v75
	v_max3_f32 v163, v163, v76, v77
	v_max3_f32 v163, v163, v78, v79
	v_max3_f32 v163, v163, v80, v81
	v_max3_f32 v163, v163, v82, v83
	v_mov_b32_e32 v164, v163
	s_nop 1
	v_permlane32_swap_b32_e32 v163, v164
	v_max_f32_e32 v164, v164, v164
	v_max_f32_e32 v163, v163, v163
	v_max_f32_e32 v163, v163, v164
	v_sub_f32_e32 v164, v163, v129
	v_cmp_ge_f32_e32 vcc, s35, v164
	v_max_f32_e32 v164, v129, v129
	v_max_f32_e32 v164, v164, v163
	v_sub_f32_e32 v163, v129, v164
	v_mul_f32_e32 v163, 0x3e0293ee, v163
	v_exp_f32_e32 v163, v163
	s_cmp_eq_u64 vcc, exec
	s_cselect_b64 s[4:5], -1, 0
	v_cndmask_b32_e64 v163, v163, 1.0, s[4:5]
	v_cmp_gt_f32_e32 vcc, 1.0, v163
	s_cbranch_vccz .LBB0_709
	s_and_saveexec_b64 s[18:19], s[44:45]
	s_cbranch_execz .LBB0_708
	ds_write_b32 v150, v163 offset:128
	s_branch .LBB0_708
